# v10 with the per-block s_setprio pairs of the GEMM K-loop removed
# speedup vs baseline: 1.0194x; 1.0094x over previous
; #define PG8_STAGE(bufoff, gbase, voff) do { _Pragma("unroll") for (int _i = 0; _i < 2; ++_i) \
;         __builtin_amdgcn_global_load_lds((const unsigned*)((const char*)(gbase) + (voff)[_i]), (PG8_LAS unsigned*)(lds + (bufoff) + ldsw + _i * 8192), 16, 0, 0); } while (0)
; #define PG8_LDA(dst, b, h) do { _Pragma("unroll") for (int m = 0; m < 4; ++m) _Pragma("unroll") for (int k = 0; k < 2; ++k) dst[m][k] = *(const PG8_LAS bf16x8*)(lds + PG8_SA(b, h) + aoff + m * 2048 + k * 1024); } while (0)
; #define PG8_LDB(dst, b, h) do { _Pragma("unroll") for (int n = 0; n < 2; ++n) _Pragma("unroll") for (int k = 0; k < 2; ++k) dst[n][k] = *(const PG8_LAS bf16x8*)(lds + PG8_SB(b, h) + boff + n * 2048 + k * 1024); } while (0)
; #define PG8_MMA(ai, bj, At, Bt) do { __builtin_amdgcn_s_setprio(1); _Pragma("unroll") for (int m = 0; m < 4; ++m) _Pragma("unroll") for (int n = 0; n < 2; ++n) _Pragma("unroll") for (int k = 0; k < 2; ++k) \
;         acc[ai][bj][m][n] = __builtin_amdgcn_mfma_f32_16x16x32_bf16(Bt[n][k], At[m][k], acc[ai][bj][m][n], 0, 0, 0); __builtin_amdgcn_s_setprio(0); } while (0)
; #define PG8_WAIT_V(n) asm volatile("s_waitcnt vmcnt(" #n ")" ::: "memory")
; #define PG8_WAIT_L(n) asm volatile("s_waitcnt lgkmcnt(" #n ")" ::: "memory")
; #define PG8_BAR __builtin_amdgcn_s_barrier()
; #define PG8_SCHED __builtin_amdgcn_sched_barrier(0)
; template <class Epi, class Sched, bool ALIGN_EPI = false, bool SP2 = false>
; __device__ __forceinline__ void gemm_phase(PG8_LAS unsigned char* lds, const Gemm g, const Sched& S, const Epi& E) {
;     ...
;             PG8_LDB(B0, 0, 0); PG8_LDB(B1, 0, 1); PG8_SCHED; PG8_LDA(At, 0, 0); PG8_STAGE(PG8_SA(1, 1), a1 + hstep, voffA);
;             PG8_WAIT_V(8); PG8_WAIT_L(0); PG8_BAR; PG8_MMA(0, 0, At, B0); PG8_MMA(0, 1, At, B1); PG8_BAR; PG8_SCHED;
;             PG8_LDA(At, 0, 1); PG8_STAGE(PG8_SB(0, 0), b2, voffB); PG8_STAGE(PG8_SB(0, 1), b2 + hstep, voffB); PG8_STAGE(PG8_SA(0, 0), a2, voffA);
;             PG8_WAIT_V(8); PG8_WAIT_L(0); PG8_BAR; PG8_MMA(1, 0, At, B0); PG8_MMA(1, 1, At, B1); PG8_BAR; PG8_SCHED;
.LBB0_307:
	s_add_i32 s26, s8, 2
	s_add_u32 s27, s2, 0x80
	s_addc_u32 s9, s3, 0
	s_add_i32 s30, 0, 0x10000
	s_cmp_eq_u32 s54, s8
	s_cselect_b32 s9, s1, s9
	s_cselect_b32 s8, s0, s27
	s_cselect_b32 s29, s25, s11
	s_cselect_b32 s28, s24, s10
	s_add_i32 s27, 0, 0x14000
	v_add_u32_e32 v140, s30, v179
	v_add_u32_e32 v156, s27, v179
	ds_read_b128 v[128:131], v140
	ds_read_b128 v[132:135], v140 offset:1024
	ds_read_b128 v[136:139], v140 offset:2048
	ds_read_b128 v[140:143], v140 offset:3072
	ds_read_b128 v[144:147], v156
	ds_read_b128 v[148:151], v156 offset:1024
	ds_read_b128 v[152:155], v156 offset:2048
	ds_read_b128 v[156:159], v156 offset:3072
	v_lshl_add_u64 v[208:209], s[2:3], 0, v[170:171]
	s_add_i32 m0, s47, 0xc000
	ds_read_b128 v[172:175], v228
	ds_read_b128 v[180:183], v228 offset:1024
	ds_read_b128 v[184:187], v228 offset:2048
	ds_read_b128 v[188:191], v228 offset:3072
	ds_read_b128 v[192:195], v228 offset:4096
	ds_read_b128 v[196:199], v228 offset:5120
	ds_read_b128 v[200:203], v228 offset:6144
	ds_read_b128 v[204:207], v228 offset:7168
	global_load_lds_dwordx4 v[208:209], off
	v_lshl_add_u64 v[208:209], s[2:3], 0, v[168:169]
	s_add_i32 m0, s47, 0xe000
	s_nop 0
	global_load_lds_dwordx4 v[208:209], off
	s_waitcnt vmcnt(8)
	s_waitcnt lgkmcnt(0)
	s_barrier
	s_waitcnt lgkmcnt(0)
	v_mfma_f32_16x16x32_bf16 v[124:127], v[128:131], v[172:175], v[124:127]
	v_mfma_f32_16x16x32_bf16 v[120:123], v[136:139], v[172:175], v[120:123]
	v_mfma_f32_16x16x32_bf16 v[108:111], v[128:131], v[184:187], v[108:111]
	v_mfma_f32_16x16x32_bf16 v[104:107], v[136:139], v[184:187], v[104:107]
	v_mfma_f32_16x16x32_bf16 v[92:95], v[128:131], v[192:195], v[92:95]
	v_mfma_f32_16x16x32_bf16 v[88:91], v[136:139], v[192:195], v[88:91]
	v_mfma_f32_16x16x32_bf16 v[76:79], v[128:131], v[200:203], v[76:79]
	v_mfma_f32_16x16x32_bf16 v[72:75], v[136:139], v[200:203], v[72:75]
	v_mfma_f32_16x16x32_bf16 v[124:127], v[132:135], v[180:183], v[124:127]
	v_mfma_f32_16x16x32_bf16 v[120:123], v[140:143], v[180:183], v[120:123]
	v_mfma_f32_16x16x32_bf16 v[108:111], v[132:135], v[188:191], v[108:111]
	v_mfma_f32_16x16x32_bf16 v[104:107], v[140:143], v[188:191], v[104:107]
	v_mfma_f32_16x16x32_bf16 v[92:95], v[132:135], v[196:199], v[92:95]
	v_mfma_f32_16x16x32_bf16 v[88:91], v[140:143], v[196:199], v[88:91]
	v_mfma_f32_16x16x32_bf16 v[76:79], v[132:135], v[204:207], v[76:79]
	v_mfma_f32_16x16x32_bf16 v[72:75], v[140:143], v[204:207], v[72:75]
	v_mfma_f32_16x16x32_bf16 v[116:119], v[144:147], v[172:175], v[116:119]
	v_mfma_f32_16x16x32_bf16 v[112:115], v[152:155], v[172:175], v[112:115]
	v_mfma_f32_16x16x32_bf16 v[100:103], v[144:147], v[184:187], v[100:103]
	v_mfma_f32_16x16x32_bf16 v[96:99], v[152:155], v[184:187], v[96:99]
	v_mfma_f32_16x16x32_bf16 v[84:87], v[144:147], v[192:195], v[84:87]
	v_mfma_f32_16x16x32_bf16 v[80:83], v[152:155], v[192:195], v[80:83]
	v_mfma_f32_16x16x32_bf16 v[68:71], v[144:147], v[200:203], v[68:71]
	v_mfma_f32_16x16x32_bf16 v[64:67], v[152:155], v[200:203], v[64:67]
	v_mfma_f32_16x16x32_bf16 v[116:119], v[148:151], v[180:183], v[116:119]
	v_mfma_f32_16x16x32_bf16 v[112:115], v[156:159], v[180:183], v[112:115]
	v_mfma_f32_16x16x32_bf16 v[100:103], v[148:151], v[188:191], v[100:103]
	v_mfma_f32_16x16x32_bf16 v[96:99], v[156:159], v[188:191], v[96:99]
	v_mfma_f32_16x16x32_bf16 v[84:87], v[148:151], v[196:199], v[84:87]
	v_mfma_f32_16x16x32_bf16 v[80:83], v[156:159], v[196:199], v[80:83]
	v_mfma_f32_16x16x32_bf16 v[68:71], v[148:151], v[204:207], v[68:71]
	v_mfma_f32_16x16x32_bf16 v[64:67], v[156:159], v[204:207], v[64:67]
	s_barrier
	s_add_i32 s30, s30, s46
	v_lshl_add_u64 v[208:209], s[28:29], 0, v[162:163]
	s_mov_b32 m0, s30
	ds_read_b128 v[172:175], v228 offset:16384
	ds_read_b128 v[180:183], v228 offset:17408
	ds_read_b128 v[184:187], v228 offset:18432
	ds_read_b128 v[188:191], v228 offset:19456
	ds_read_b128 v[192:195], v228 offset:20480
	ds_read_b128 v[196:199], v228 offset:21504
	ds_read_b128 v[200:203], v228 offset:22528
	ds_read_b128 v[204:207], v228 offset:23552
	global_load_lds_dwordx4 v[208:209], off
	s_add_i32 m0, s30, 0x2000
	v_lshl_add_u64 v[210:211], s[28:29], 0, v[166:167]
	s_add_u32 s28, s28, s88
	s_addc_u32 s29, s29, 0
	s_add_i32 s27, s27, s46
	global_load_lds_dwordx4 v[210:211], off
	v_lshl_add_u64 v[212:213], s[28:29], 0, v[162:163]
	s_mov_b32 m0, s27
	v_lshl_add_u64 v[214:215], s[28:29], 0, v[166:167]
	global_load_lds_dwordx4 v[212:213], off
	s_add_i32 m0, s27, 0x2000
	v_lshl_add_u64 v[230:231], s[8:9], 0, v[160:161]
	global_load_lds_dwordx4 v[214:215], off
	s_mov_b32 m0, s47
	v_lshl_add_u64 v[232:233], s[8:9], 0, v[164:165]
	global_load_lds_dwordx4 v[230:231], off
	s_mov_b32 m0, s48
	s_nop 0
	global_load_lds_dwordx4 v[232:233], off
	s_waitcnt vmcnt(8)
	s_waitcnt lgkmcnt(0)
	s_barrier
; #define PG8_STAGE(bufoff, gbase, voff) do { _Pragma("unroll") for (int _i = 0; _i < 2; ++_i) \
;         __builtin_amdgcn_global_load_lds((const unsigned*)((const char*)(gbase) + (voff)[_i]), (PG8_LAS unsigned*)(lds + (bufoff) + ldsw + _i * 8192), 16, 0, 0); } while (0)
; #define PG8_LDA(dst, b, h) do { _Pragma("unroll") for (int m = 0; m < 4; ++m) _Pragma("unroll") for (int k = 0; k < 2; ++k) dst[m][k] = *(const PG8_LAS bf16x8*)(lds + PG8_SA(b, h) + aoff + m * 2048 + k * 1024); } while (0)
; #define PG8_LDB(dst, b, h) do { _Pragma("unroll") for (int n = 0; n < 2; ++n) _Pragma("unroll") for (int k = 0; k < 2; ++k) dst[n][k] = *(const PG8_LAS bf16x8*)(lds + PG8_SB(b, h) + boff + n * 2048 + k * 1024); } while (0)
; #define PG8_MMA(ai, bj, At, Bt) do { __builtin_amdgcn_s_setprio(1); _Pragma("unroll") for (int m = 0; m < 4; ++m) _Pragma("unroll") for (int n = 0; n < 2; ++n) _Pragma("unroll") for (int k = 0; k < 2; ++k) \
;         acc[ai][bj][m][n] = __builtin_amdgcn_mfma_f32_16x16x32_bf16(Bt[n][k], At[m][k], acc[ai][bj][m][n], 0, 0, 0); __builtin_amdgcn_s_setprio(0); } while (0)
; #define PG8_WAIT_V(n) asm volatile("s_waitcnt vmcnt(" #n ")" ::: "memory")
; #define PG8_WAIT_L(n) asm volatile("s_waitcnt lgkmcnt(" #n ")" ::: "memory")
; #define PG8_BAR __builtin_amdgcn_s_barrier()
; #define PG8_SCHED __builtin_amdgcn_sched_barrier(0)
; template <class Epi, class Sched, bool ALIGN_EPI = false, bool SP2 = false>
; __device__ __forceinline__ void gemm_phase(PG8_LAS unsigned char* lds, const Gemm g, const Sched& S, const Epi& E) {
;     ...
;             PG8_WAIT_V(8); PG8_WAIT_L(0); PG8_BAR; PG8_MMA(0, 0, At, B0); PG8_MMA(0, 1, At, B1); PG8_BAR; PG8_SCHED;
;             PG8_LDA(At, 0, 1); PG8_STAGE(PG8_SB(0, 0), b2, voffB); PG8_STAGE(PG8_SB(0, 1), b2 + hstep, voffB); PG8_STAGE(PG8_SA(0, 0), a2, voffA);
;             PG8_WAIT_V(8); PG8_WAIT_L(0); PG8_BAR; PG8_MMA(1, 0, At, B0); PG8_MMA(1, 1, At, B1); PG8_BAR; PG8_SCHED;
;             PG8_LDB(B0, 1, 0); PG8_LDB(B1, 1, 1); PG8_SCHED; PG8_LDA(At, 1, 0); PG8_STAGE(PG8_SA(0, 1), a2 + hstep, voffA);
;             PG8_WAIT_V(8); PG8_WAIT_L(0); PG8_BAR; PG8_MMA(0, 0, At, B0); PG8_MMA(0, 1, At, B1); PG8_BAR; PG8_SCHED;
	s_waitcnt lgkmcnt(0)
	v_mfma_f32_16x16x32_bf16 v[60:63], v[128:131], v[172:175], v[60:63]
	v_mfma_f32_16x16x32_bf16 v[56:59], v[136:139], v[172:175], v[56:59]
	v_mfma_f32_16x16x32_bf16 v[44:47], v[128:131], v[184:187], v[44:47]
	v_mfma_f32_16x16x32_bf16 v[40:43], v[136:139], v[184:187], v[40:43]
	v_mfma_f32_16x16x32_bf16 v[28:31], v[128:131], v[192:195], v[28:31]
	v_mfma_f32_16x16x32_bf16 v[24:27], v[136:139], v[192:195], v[24:27]
	v_mfma_f32_16x16x32_bf16 v[12:15], v[128:131], v[200:203], v[12:15]
	v_mfma_f32_16x16x32_bf16 v[8:11], v[136:139], v[200:203], v[8:11]
	v_mfma_f32_16x16x32_bf16 v[60:63], v[132:135], v[180:183], v[60:63]
	v_mfma_f32_16x16x32_bf16 v[56:59], v[140:143], v[180:183], v[56:59]
	v_mfma_f32_16x16x32_bf16 v[44:47], v[132:135], v[188:191], v[44:47]
	v_mfma_f32_16x16x32_bf16 v[40:43], v[140:143], v[188:191], v[40:43]
	v_mfma_f32_16x16x32_bf16 v[28:31], v[132:135], v[196:199], v[28:31]
	v_mfma_f32_16x16x32_bf16 v[24:27], v[140:143], v[196:199], v[24:27]
	v_mfma_f32_16x16x32_bf16 v[12:15], v[132:135], v[204:207], v[12:15]
	v_mfma_f32_16x16x32_bf16 v[8:11], v[140:143], v[204:207], v[8:11]
	v_mfma_f32_16x16x32_bf16 v[52:55], v[144:147], v[172:175], v[52:55]
	v_mfma_f32_16x16x32_bf16 v[48:51], v[152:155], v[172:175], v[48:51]
	v_mfma_f32_16x16x32_bf16 v[36:39], v[144:147], v[184:187], v[36:39]
	v_mfma_f32_16x16x32_bf16 v[32:35], v[152:155], v[184:187], v[32:35]
	v_mfma_f32_16x16x32_bf16 v[20:23], v[144:147], v[192:195], v[20:23]
	v_mfma_f32_16x16x32_bf16 v[16:19], v[152:155], v[192:195], v[16:19]
	v_mfma_f32_16x16x32_bf16 v[4:7], v[144:147], v[200:203], v[4:7]
	v_mfma_f32_16x16x32_bf16 v[0:3], v[152:155], v[200:203], v[0:3]
	v_mfma_f32_16x16x32_bf16 v[52:55], v[148:151], v[180:183], v[52:55]
	v_mfma_f32_16x16x32_bf16 v[48:51], v[156:159], v[180:183], v[48:51]
	v_mfma_f32_16x16x32_bf16 v[36:39], v[148:151], v[188:191], v[36:39]
	v_mfma_f32_16x16x32_bf16 v[32:35], v[156:159], v[188:191], v[32:35]
	v_mfma_f32_16x16x32_bf16 v[20:23], v[148:151], v[196:199], v[20:23]
	v_mfma_f32_16x16x32_bf16 v[16:19], v[156:159], v[196:199], v[16:19]
	v_mfma_f32_16x16x32_bf16 v[4:7], v[148:151], v[204:207], v[4:7]
	v_mfma_f32_16x16x32_bf16 v[0:3], v[156:159], v[204:207], v[0:3]
	s_barrier
	s_add_i32 s27, 0, 0x18000
	s_add_i32 s28, 0, 0x1c000
	v_add_u32_e32 v140, s27, v179
	v_add_u32_e32 v156, s28, v179
	ds_read_b128 v[128:131], v140
	ds_read_b128 v[132:135], v140 offset:1024
	ds_read_b128 v[136:139], v140 offset:2048
	ds_read_b128 v[140:143], v140 offset:3072
	ds_read_b128 v[144:147], v156
	ds_read_b128 v[148:151], v156 offset:1024
	ds_read_b128 v[152:155], v156 offset:2048
	ds_read_b128 v[156:159], v156 offset:3072
	s_add_u32 s8, s8, s88
	s_addc_u32 s9, s9, 0
	s_mov_b32 m0, s49
	v_lshl_add_u64 v[234:235], s[8:9], 0, v[160:161]
	ds_read_b128 v[172:175], v228 offset:32768
	ds_read_b128 v[180:183], v228 offset:33792
	ds_read_b128 v[184:187], v228 offset:34816
	ds_read_b128 v[188:191], v228 offset:35840
	ds_read_b128 v[192:195], v228 offset:36864
	ds_read_b128 v[196:199], v228 offset:37888
	ds_read_b128 v[200:203], v228 offset:38912
	ds_read_b128 v[204:207], v228 offset:39936
	global_load_lds_dwordx4 v[234:235], off
	v_lshl_add_u64 v[234:235], s[8:9], 0, v[164:165]
	s_mov_b32 m0, s50
	s_nop 0
	global_load_lds_dwordx4 v[234:235], off
	s_waitcnt vmcnt(8)
	s_waitcnt lgkmcnt(0)
	s_barrier
	s_waitcnt lgkmcnt(0)
	v_mfma_f32_16x16x32_bf16 v[124:127], v[128:131], v[172:175], v[124:127]
	v_mfma_f32_16x16x32_bf16 v[120:123], v[136:139], v[172:175], v[120:123]
	v_mfma_f32_16x16x32_bf16 v[108:111], v[128:131], v[184:187], v[108:111]
	v_mfma_f32_16x16x32_bf16 v[104:107], v[136:139], v[184:187], v[104:107]
	v_mfma_f32_16x16x32_bf16 v[92:95], v[128:131], v[192:195], v[92:95]
	v_mfma_f32_16x16x32_bf16 v[88:91], v[136:139], v[192:195], v[88:91]
	v_mfma_f32_16x16x32_bf16 v[76:79], v[128:131], v[200:203], v[76:79]
	v_mfma_f32_16x16x32_bf16 v[72:75], v[136:139], v[200:203], v[72:75]
	v_mfma_f32_16x16x32_bf16 v[124:127], v[132:135], v[180:183], v[124:127]
	v_mfma_f32_16x16x32_bf16 v[120:123], v[140:143], v[180:183], v[120:123]
	v_mfma_f32_16x16x32_bf16 v[108:111], v[132:135], v[188:191], v[108:111]
	v_mfma_f32_16x16x32_bf16 v[104:107], v[140:143], v[188:191], v[104:107]
	v_mfma_f32_16x16x32_bf16 v[92:95], v[132:135], v[196:199], v[92:95]
	v_mfma_f32_16x16x32_bf16 v[88:91], v[140:143], v[196:199], v[88:91]
	v_mfma_f32_16x16x32_bf16 v[76:79], v[132:135], v[204:207], v[76:79]
	v_mfma_f32_16x16x32_bf16 v[72:75], v[140:143], v[204:207], v[72:75]
	v_mfma_f32_16x16x32_bf16 v[116:119], v[144:147], v[172:175], v[116:119]
	v_mfma_f32_16x16x32_bf16 v[112:115], v[152:155], v[172:175], v[112:115]
	v_mfma_f32_16x16x32_bf16 v[100:103], v[144:147], v[184:187], v[100:103]
	v_mfma_f32_16x16x32_bf16 v[96:99], v[152:155], v[184:187], v[96:99]
	v_mfma_f32_16x16x32_bf16 v[84:87], v[144:147], v[192:195], v[84:87]
	v_mfma_f32_16x16x32_bf16 v[80:83], v[152:155], v[192:195], v[80:83]
	v_mfma_f32_16x16x32_bf16 v[68:71], v[144:147], v[200:203], v[68:71]
	v_mfma_f32_16x16x32_bf16 v[64:67], v[152:155], v[200:203], v[64:67]
	v_mfma_f32_16x16x32_bf16 v[116:119], v[148:151], v[180:183], v[116:119]
	v_mfma_f32_16x16x32_bf16 v[112:115], v[156:159], v[180:183], v[112:115]
	v_mfma_f32_16x16x32_bf16 v[100:103], v[148:151], v[188:191], v[100:103]
	v_mfma_f32_16x16x32_bf16 v[96:99], v[156:159], v[188:191], v[96:99]
	v_mfma_f32_16x16x32_bf16 v[84:87], v[148:151], v[196:199], v[84:87]
	v_mfma_f32_16x16x32_bf16 v[80:83], v[156:159], v[196:199], v[80:83]
	v_mfma_f32_16x16x32_bf16 v[68:71], v[148:151], v[204:207], v[68:71]
	v_mfma_f32_16x16x32_bf16 v[64:67], v[156:159], v[204:207], v[64:67]
	s_barrier
; #define PG8_STAGE(bufoff, gbase, voff) do { _Pragma("unroll") for (int _i = 0; _i < 2; ++_i) \
;         __builtin_amdgcn_global_load_lds((const unsigned*)((const char*)(gbase) + (voff)[_i]), (PG8_LAS unsigned*)(lds + (bufoff) + ldsw + _i * 8192), 16, 0, 0); } while (0)
; #define PG8_LDA(dst, b, h) do { _Pragma("unroll") for (int m = 0; m < 4; ++m) _Pragma("unroll") for (int k = 0; k < 2; ++k) dst[m][k] = *(const PG8_LAS bf16x8*)(lds + PG8_SA(b, h) + aoff + m * 2048 + k * 1024); } while (0)
; #define PG8_LDB(dst, b, h) do { _Pragma("unroll") for (int n = 0; n < 2; ++n) _Pragma("unroll") for (int k = 0; k < 2; ++k) dst[n][k] = *(const PG8_LAS bf16x8*)(lds + PG8_SB(b, h) + boff + n * 2048 + k * 1024); } while (0)
; template <class Epi, class Sched, bool ALIGN_EPI = false, bool SP2 = false>
; __device__ __forceinline__ void gemm_phase(PG8_LAS unsigned char* lds, const Gemm g, const Sched& S, const Epi& E) {
;     ...
;         for (int t = 0; t < nt; t += 2) {
;             const bool last = (t == nt - 2);
;             const char* a1 = cA + (size_t)(t + 1) * kstep;
;             const char* a2 = last ? nA : cA + (size_t)(t + 2) * kstep; const char* b2 = last ? nB : cB + (size_t)(t + 2) * kstep;
;             const char* a3 = a2 + kstep; const char* b3 = b2 + kstep;
;             if (last && has_next) S.a_ready(nxt);
;             if constexpr (SP2) {
;             PG8_LDB(B0, 0, 0); PG8_LDB(B1, 0, 1); PG8_SCHED; PG8_LDA(At, 0, 0); PG8_STAGE(PG8_SA(1, 1), a1 + hstep, voffA);
;             PG8_WAIT_V(8); PG8_WAIT_L(0); PG8_BAR; PG8_MMA(0, 0, At, B0); PG8_MMA(0, 1, At, B1); PG8_BAR; PG8_SCHED;
;             PG8_LDA(At, 0, 1); PG8_STAGE(PG8_SB(0, 0), b2, voffB); PG8_STAGE(PG8_SB(0, 1), b2 + hstep, voffB); PG8_STAGE(PG8_SA(0, 0), a2, voffA);
;             PG8_WAIT_V(8); PG8_WAIT_L(0); PG8_BAR; PG8_MMA(1, 0, At, B0); PG8_MMA(1, 1, At, B1); PG8_BAR; PG8_SCHED;
;             PG8_LDB(B0, 1, 0); PG8_LDB(B1, 1, 1); PG8_SCHED; PG8_LDA(At, 1, 0); PG8_STAGE(PG8_SA(0, 1), a2 + hstep, voffA);
;             PG8_WAIT_V(8); PG8_WAIT_L(0); PG8_BAR; PG8_MMA(0, 0, At, B0); PG8_MMA(0, 1, At, B1); PG8_BAR; PG8_SCHED;
;             PG8_LDA(At, 1, 1); PG8_STAGE(PG8_SB(1, 0), b3, voffB); PG8_STAGE(PG8_SB(1, 1), b3 + hstep, voffB); PG8_STAGE(PG8_SA(1, 0), a3, voffA);
;             PG8_WAIT_V(8); PG8_WAIT_L(0); PG8_BAR; PG8_MMA(1, 0, At, B0); PG8_MMA(1, 1, At, B1); PG8_BAR; PG8_SCHED;
	s_add_i32 s8, s27, s46
	v_lshl_add_u64 v[208:209], v[208:209], 0, s[94:95]
	s_mov_b32 m0, s8
	ds_read_b128 v[172:175], v228 offset:49152
	ds_read_b128 v[180:183], v228 offset:50176
	ds_read_b128 v[184:187], v228 offset:51200
	ds_read_b128 v[188:191], v228 offset:52224
	ds_read_b128 v[192:195], v228 offset:53248
	ds_read_b128 v[196:199], v228 offset:54272
	ds_read_b128 v[200:203], v228 offset:55296
	ds_read_b128 v[204:207], v228 offset:56320
	global_load_lds_dwordx4 v[208:209], off
	v_lshl_add_u64 v[208:209], v[210:211], 0, s[94:95]
	s_add_i32 m0, s8, 0x2000
	s_add_i32 s8, s28, s46
	global_load_lds_dwordx4 v[208:209], off
	v_lshl_add_u64 v[208:209], v[212:213], 0, s[94:95]
	s_mov_b32 m0, s8
	s_nop 0
	global_load_lds_dwordx4 v[208:209], off
	v_lshl_add_u64 v[208:209], v[214:215], 0, s[94:95]
	s_add_i32 m0, s8, 0x2000
	s_nop 0
	global_load_lds_dwordx4 v[208:209], off
	v_lshl_add_u64 v[208:209], v[230:231], 0, s[94:95]
	s_mov_b32 m0, s52
	s_nop 0
	global_load_lds_dwordx4 v[208:209], off
	v_lshl_add_u64 v[208:209], v[232:233], 0, s[94:95]
	s_mov_b32 m0, s53
	s_nop 0
	global_load_lds_dwordx4 v[208:209], off
	s_waitcnt vmcnt(8)
	s_waitcnt lgkmcnt(0)
	s_barrier
	s_waitcnt lgkmcnt(0)
	v_mfma_f32_16x16x32_bf16 v[60:63], v[128:131], v[172:175], v[60:63]
	v_mfma_f32_16x16x32_bf16 v[56:59], v[136:139], v[172:175], v[56:59]
	v_mfma_f32_16x16x32_bf16 v[44:47], v[128:131], v[184:187], v[44:47]
	v_mfma_f32_16x16x32_bf16 v[40:43], v[136:139], v[184:187], v[40:43]
	v_mfma_f32_16x16x32_bf16 v[28:31], v[128:131], v[192:195], v[28:31]
	v_mfma_f32_16x16x32_bf16 v[24:27], v[136:139], v[192:195], v[24:27]
	v_mfma_f32_16x16x32_bf16 v[12:15], v[128:131], v[200:203], v[12:15]
	v_mfma_f32_16x16x32_bf16 v[8:11], v[136:139], v[200:203], v[8:11]
	v_mfma_f32_16x16x32_bf16 v[60:63], v[132:135], v[180:183], v[60:63]
	v_mfma_f32_16x16x32_bf16 v[56:59], v[140:143], v[180:183], v[56:59]
	v_mfma_f32_16x16x32_bf16 v[44:47], v[132:135], v[188:191], v[44:47]
	v_mfma_f32_16x16x32_bf16 v[40:43], v[140:143], v[188:191], v[40:43]
	v_mfma_f32_16x16x32_bf16 v[28:31], v[132:135], v[196:199], v[28:31]
	v_mfma_f32_16x16x32_bf16 v[24:27], v[140:143], v[196:199], v[24:27]
	v_mfma_f32_16x16x32_bf16 v[12:15], v[132:135], v[204:207], v[12:15]
	v_mfma_f32_16x16x32_bf16 v[8:11], v[140:143], v[204:207], v[8:11]
	v_mfma_f32_16x16x32_bf16 v[52:55], v[144:147], v[172:175], v[52:55]
	v_mfma_f32_16x16x32_bf16 v[48:51], v[152:155], v[172:175], v[48:51]
	v_mfma_f32_16x16x32_bf16 v[36:39], v[144:147], v[184:187], v[36:39]
	v_mfma_f32_16x16x32_bf16 v[32:35], v[152:155], v[184:187], v[32:35]
	v_mfma_f32_16x16x32_bf16 v[20:23], v[144:147], v[192:195], v[20:23]
	v_mfma_f32_16x16x32_bf16 v[16:19], v[152:155], v[192:195], v[16:19]
	v_mfma_f32_16x16x32_bf16 v[4:7], v[144:147], v[200:203], v[4:7]
	v_mfma_f32_16x16x32_bf16 v[0:3], v[152:155], v[200:203], v[0:3]
	v_mfma_f32_16x16x32_bf16 v[52:55], v[148:151], v[180:183], v[52:55]
	v_mfma_f32_16x16x32_bf16 v[48:51], v[156:159], v[180:183], v[48:51]
	v_mfma_f32_16x16x32_bf16 v[36:39], v[148:151], v[188:191], v[36:39]
	v_mfma_f32_16x16x32_bf16 v[32:35], v[156:159], v[188:191], v[32:35]
	v_mfma_f32_16x16x32_bf16 v[20:23], v[148:151], v[196:199], v[20:23]
	v_mfma_f32_16x16x32_bf16 v[16:19], v[156:159], v[196:199], v[16:19]
	v_mfma_f32_16x16x32_bf16 v[4:7], v[148:151], v[204:207], v[4:7]
	v_mfma_f32_16x16x32_bf16 v[0:3], v[156:159], v[204:207], v[0:3]
	s_barrier
	s_add_u32 s10, s10, 0x100
	s_addc_u32 s11, s11, 0
	s_add_u32 s2, s2, 0x100
	s_addc_u32 s3, s3, 0
	s_cmp_ge_u32 s26, s51
	s_mov_b32 s8, s26
	s_cbranch_scc0 .LBB0_307
	s_and_b64 vcc, exec, s[22:23]
	s_cbranch_vccz .LBB0_310
	s_barrier
